# speedup vs baseline: 1.0089x; 1.0089x over previous
; __device__ __forceinline__ unsigned cvt_pk_bf16(float lo, float hi) { unsigned r; asm volatile("v_cvt_pk_bf16_f32 %0, %1, %2" : "=v"(r) : "v"(lo), "v"(hi)); return r; }
;     __device__ __forceinline__ void operator()(const f32x4 (&acc)[2][2][4][2], const Unit& u, int wr, int wc, int fr, int fq) const {
;     ...
;         const int col0 = u.pn * HALF + wc * 32 + 8 * fq;
; #pragma unroll
;         for (int ai = 0; ai < 2; ++ai)
; #pragma unroll
;             for (int m = 0; m < 4; ++m) { bf16_t* rowp = O + (size_t)(row0 + ai * HALF + m * 16) * ldc + col0;
;                 f32x2 h[4];
; #pragma unroll
;                 for (int n = 0; n < 2; ++n)
; #pragma unroll
;                     for (int j = 0; j < 2; ++j) { const f32x2 g = {acc[ai][0][m][n][2 * j], acc[ai][0][m][n][2 * j + 1]}, up = {acc[ai][1][m][n][2 * j], acc[ai][1][m][n][2 * j + 1]};
;                         const f32x2 t = g * (-1.44269504089f); f32x2 e; e.x = __builtin_amdgcn_exp2f(t.x); e.y = __builtin_amdgcn_exp2f(t.y);
;                         const f32x2 d = e + 1.0f; f32x2 r; r.x = __builtin_amdgcn_rcpf(d.x); r.y = __builtin_amdgcn_rcpf(d.y);
;                         h[n * 2 + j] = (g * r) * up; }
;                 u32x4 w; w.x = cvt_pk_bf16(h[0].x, h[0].y); w.y = cvt_pk_bf16(h[1].x, h[1].y); w.z = cvt_pk_bf16(h[2].x, h[2].y); w.w = cvt_pk_bf16(h[3].x, h[3].y);
;                 *(u32x4*)rowp = w; }
.LBB0_362:
	v_lshrrev_b32_e32 v254, 2, v206
	v_and_b32_e32 v255, 15, v206
	v_sub_u32_e32 v252, v254, v255
	v_mul_lo_u32 v252, v252, s20
	v_lshlrev_b32_e32 v252, 1, v252
	v_and_b32_e32 v253, 3, v206
	v_lshrrev_b32_e32 v255, 4, v206
	v_sub_u32_e32 v253, v253, v255
	v_lshl_add_u32 v252, v253, 4, v252
	v_ashrrev_i32_e32 v253, 31, v252
	v_lshrrev_b32_e32 v255, 6, v180
	v_mul_u32_u24_e32 v255, 0x500, v255
	v_add_u32_e32 v255, 0x20000, v255
	v_and_b32_e32 v244, 15, v206
	v_mul_u32_u24_e32 v244, 0x50, v244
	v_lshrrev_b32_e32 v245, 4, v206
	v_lshl_add_u32 v244, v245, 4, v244
	v_add_u32_e32 v244, v244, v255
	v_mul_u32_u24_e32 v245, 0x50, v254
	v_and_b32_e32 v254, 3, v206
	v_lshl_add_u32 v245, v254, 4, v245
	v_add_u32_e32 v245, v245, v255
	v_lshl_add_u32 v148, s31, 8, v144
	s_cmp_lt_i32 s30, 0
	s_mov_b64 s[38:39], -1
	s_mov_b32 s60, 0x14000
	s_cbranch_scc0 .LBB0_369
	v_mad_i64_i32 v[140:141], s[18:19], s20, v148, 0
	v_lshl_add_u64 v[140:141], v[140:141], 1, s[8:9]
	s_and_b64 vcc, exec, s[26:27]
	v_or_b32_e32 v155, 16, v148
	v_or_b32_e32 v154, 32, v148
	v_or_b32_e32 v153, 48, v148
	v_add_u32_e32 v152, 0x80, v148
	v_add_u32_e32 v151, 0x90, v148
	v_add_u32_e32 v150, 0xa0, v148
	v_add_u32_e32 v149, 0xb0, v148
	s_cbranch_vccz .LBB0_365
	v_pk_mul_f32 v[156:157], v[126:127], s[92:93] op_sel_hi:[1,0]
	v_pk_mul_f32 v[158:159], v[128:129], s[92:93] op_sel_hi:[1,0]
	v_exp_f32_e32 v156, v156
	v_exp_f32_e32 v157, v157
	v_exp_f32_e32 v158, v158
	v_exp_f32_e32 v159, v159
	v_pk_mul_f32 v[160:161], v[122:123], s[92:93] op_sel_hi:[1,0]
	v_pk_mul_f32 v[162:163], v[124:125], s[92:93] op_sel_hi:[1,0]
	v_exp_f32_e32 v160, v160
	v_exp_f32_e32 v161, v161
	v_exp_f32_e32 v162, v162
	v_exp_f32_e32 v163, v163
	v_pk_add_f32 v[156:157], v[156:157], 1.0 op_sel_hi:[1,0]
	v_pk_add_f32 v[158:159], v[158:159], 1.0 op_sel_hi:[1,0]
	v_rcp_f32_e32 v156, v156
	v_rcp_f32_e32 v157, v157
	v_rcp_f32_e32 v158, v158
	v_rcp_f32_e32 v159, v159
	v_pk_add_f32 v[160:161], v[160:161], 1.0 op_sel_hi:[1,0]
	v_pk_add_f32 v[162:163], v[162:163], 1.0 op_sel_hi:[1,0]
	v_rcp_f32_e32 v160, v160
	v_rcp_f32_e32 v161, v161
	v_rcp_f32_e32 v162, v162
	v_rcp_f32_e32 v163, v163
	v_lshl_or_b32 v142, s67, 7, v146
	v_ashrrev_i32_e32 v143, 31, v142
	v_pk_mul_f32 v[156:157], v[126:127], v[156:157]
	v_pk_mul_f32 v[158:159], v[128:129], v[158:159]
	v_pk_mul_f32 v[156:157], v[114:115], v[156:157]
	v_pk_mul_f32 v[158:159], v[116:117], v[158:159]
	v_pk_mul_f32 v[160:161], v[122:123], v[160:161]
	v_pk_mul_f32 v[162:163], v[124:125], v[162:163]
	v_lshlrev_b64 v[142:143], 1, v[142:143]
	v_pk_mul_f32 v[160:161], v[106:107], v[160:161]
	v_pk_mul_f32 v[162:163], v[108:109], v[162:163]
	v_lshl_add_u64 v[164:165], v[140:141], 0, v[142:143]
	v_cvt_pk_bf16_f32 v156, v156, v157
	v_cvt_pk_bf16_f32 v157, v158, v159
	v_cvt_pk_bf16_f32 v158, v160, v161
	v_cvt_pk_bf16_f32 v159, v162, v163
	ds_write_b128 v244, v[156:159]
	v_lshl_add_u64 v[246:247], v[164:165], 0, v[252:253]
	s_waitcnt lgkmcnt(0)
	ds_read_b128 v[248:251], v245
	v_pk_mul_f32 v[160:161], v[120:121], s[92:93] op_sel_hi:[1,0]
	v_pk_mul_f32 v[162:163], v[110:111], s[92:93] op_sel_hi:[1,0]
	v_pk_mul_f32 v[158:159], v[118:119], s[92:93] op_sel_hi:[1,0]
	v_pk_mul_f32 v[164:165], v[112:113], s[92:93] op_sel_hi:[1,0]
	v_exp_f32_e32 v158, v158
	v_exp_f32_e32 v159, v159
	v_exp_f32_e32 v160, v160
	v_exp_f32_e32 v161, v161
	v_exp_f32_e32 v162, v162
	v_exp_f32_e32 v163, v163
	v_exp_f32_e32 v164, v164
	v_exp_f32_e32 v165, v165
	v_pk_add_f32 v[158:159], v[158:159], 1.0 op_sel_hi:[1,0]
	v_pk_add_f32 v[160:161], v[160:161], 1.0 op_sel_hi:[1,0]
	v_rcp_f32_e32 v158, v158
	v_rcp_f32_e32 v159, v159
	v_pk_add_f32 v[162:163], v[162:163], 1.0 op_sel_hi:[1,0]
	v_pk_add_f32 v[164:165], v[164:165], 1.0 op_sel_hi:[1,0]
	v_rcp_f32_e32 v160, v160
	v_rcp_f32_e32 v161, v161
	v_rcp_f32_e32 v162, v162
	v_rcp_f32_e32 v163, v163
	v_rcp_f32_e32 v164, v164
	v_rcp_f32_e32 v165, v165
	v_mad_i64_i32 v[156:157], s[18:19], s20, v155, 0
	v_pk_mul_f32 v[158:159], v[118:119], v[158:159]
	v_lshl_add_u64 v[156:157], v[156:157], 1, s[8:9]
	v_pk_mul_f32 v[158:159], v[98:99], v[158:159]
	v_pk_mul_f32 v[160:161], v[120:121], v[160:161]
	v_pk_mul_f32 v[162:163], v[110:111], v[162:163]
	v_pk_mul_f32 v[164:165], v[112:113], v[164:165]
	v_pk_mul_f32 v[160:161], v[100:101], v[160:161]
	v_pk_mul_f32 v[162:163], v[90:91], v[162:163]
	v_pk_mul_f32 v[164:165], v[92:93], v[164:165]
	v_lshl_add_u64 v[166:167], v[156:157], 0, v[142:143]
	v_cvt_pk_bf16_f32 v156, v158, v159
	v_cvt_pk_bf16_f32 v157, v160, v161
	v_cvt_pk_bf16_f32 v158, v162, v163
	v_cvt_pk_bf16_f32 v159, v164, v165
	s_waitcnt lgkmcnt(0)
	global_store_dwordx4 v[246:247], v[248:251], off
	ds_write_b128 v244, v[156:159]
	v_lshl_add_u64 v[246:247], v[166:167], 0, v[252:253]
	s_waitcnt lgkmcnt(0)
	ds_read_b128 v[248:251], v245
	v_pk_mul_f32 v[160:161], v[104:105], s[92:93] op_sel_hi:[1,0]
	v_pk_mul_f32 v[162:163], v[94:95], s[92:93] op_sel_hi:[1,0]
	v_pk_mul_f32 v[158:159], v[102:103], s[92:93] op_sel_hi:[1,0]
	v_pk_mul_f32 v[164:165], v[96:97], s[92:93] op_sel_hi:[1,0]
	v_exp_f32_e32 v158, v158
	v_exp_f32_e32 v159, v159
	v_exp_f32_e32 v160, v160
	v_exp_f32_e32 v161, v161
	v_exp_f32_e32 v162, v162
	v_exp_f32_e32 v163, v163
	v_exp_f32_e32 v164, v164
	v_exp_f32_e32 v165, v165
	v_pk_add_f32 v[158:159], v[158:159], 1.0 op_sel_hi:[1,0]
	v_pk_add_f32 v[160:161], v[160:161], 1.0 op_sel_hi:[1,0]
	v_rcp_f32_e32 v158, v158
	v_rcp_f32_e32 v159, v159
	v_pk_add_f32 v[162:163], v[162:163], 1.0 op_sel_hi:[1,0]
	v_pk_add_f32 v[164:165], v[164:165], 1.0 op_sel_hi:[1,0]
	v_rcp_f32_e32 v160, v160
	v_rcp_f32_e32 v161, v161
	v_rcp_f32_e32 v162, v162
	v_rcp_f32_e32 v163, v163
	v_rcp_f32_e32 v164, v164
	v_rcp_f32_e32 v165, v165
	v_mad_i64_i32 v[156:157], s[18:19], s20, v154, 0
	v_pk_mul_f32 v[158:159], v[102:103], v[158:159]
	v_lshl_add_u64 v[156:157], v[156:157], 1, s[8:9]
	v_pk_mul_f32 v[158:159], v[82:83], v[158:159]
	v_pk_mul_f32 v[160:161], v[104:105], v[160:161]
	v_pk_mul_f32 v[162:163], v[94:95], v[162:163]
	v_pk_mul_f32 v[164:165], v[96:97], v[164:165]
	v_pk_mul_f32 v[160:161], v[84:85], v[160:161]
	v_pk_mul_f32 v[162:163], v[74:75], v[162:163]
	v_pk_mul_f32 v[164:165], v[76:77], v[164:165]
	v_lshl_add_u64 v[166:167], v[156:157], 0, v[142:143]
	v_cvt_pk_bf16_f32 v156, v158, v159
	v_cvt_pk_bf16_f32 v157, v160, v161
	v_cvt_pk_bf16_f32 v158, v162, v163
	v_cvt_pk_bf16_f32 v159, v164, v165
	s_waitcnt lgkmcnt(0)
; __device__ __forceinline__ unsigned cvt_pk_bf16(float lo, float hi) { unsigned r; asm volatile("v_cvt_pk_bf16_f32 %0, %1, %2" : "=v"(r) : "v"(lo), "v"(hi)); return r; }
;     __device__ __forceinline__ void operator()(const f32x4 (&acc)[2][2][4][2], const Unit& u, int wr, int wc, int fr, int fq) const {
;     ...
;         const int col0 = u.pn * HALF + wc * 32 + 8 * fq;
; #pragma unroll
;         for (int ai = 0; ai < 2; ++ai)
; #pragma unroll
;             for (int m = 0; m < 4; ++m) { bf16_t* rowp = O + (size_t)(row0 + ai * HALF + m * 16) * ldc + col0;
;                 f32x2 h[4];
; #pragma unroll
;                 for (int n = 0; n < 2; ++n)
; #pragma unroll
;                     for (int j = 0; j < 2; ++j) { const f32x2 g = {acc[ai][0][m][n][2 * j], acc[ai][0][m][n][2 * j + 1]}, up = {acc[ai][1][m][n][2 * j], acc[ai][1][m][n][2 * j + 1]};
;                         const f32x2 t = g * (-1.44269504089f); f32x2 e; e.x = __builtin_amdgcn_exp2f(t.x); e.y = __builtin_amdgcn_exp2f(t.y);
;                         const f32x2 d = e + 1.0f; f32x2 r; r.x = __builtin_amdgcn_rcpf(d.x); r.y = __builtin_amdgcn_rcpf(d.y);
;                         h[n * 2 + j] = (g * r) * up; }
;                 u32x4 w; w.x = cvt_pk_bf16(h[0].x, h[0].y); w.y = cvt_pk_bf16(h[1].x, h[1].y); w.z = cvt_pk_bf16(h[2].x, h[2].y); w.w = cvt_pk_bf16(h[3].x, h[3].y);
;                 *(u32x4*)rowp = w; }
	global_store_dwordx4 v[246:247], v[248:251], off
	ds_write_b128 v244, v[156:159]
	v_lshl_add_u64 v[246:247], v[166:167], 0, v[252:253]
	s_waitcnt lgkmcnt(0)
	ds_read_b128 v[248:251], v245
	v_pk_mul_f32 v[160:161], v[88:89], s[92:93] op_sel_hi:[1,0]
	v_pk_mul_f32 v[162:163], v[78:79], s[92:93] op_sel_hi:[1,0]
	v_pk_mul_f32 v[158:159], v[86:87], s[92:93] op_sel_hi:[1,0]
	v_pk_mul_f32 v[164:165], v[80:81], s[92:93] op_sel_hi:[1,0]
	v_exp_f32_e32 v158, v158
	v_exp_f32_e32 v159, v159
	v_exp_f32_e32 v160, v160
	v_exp_f32_e32 v161, v161
	v_exp_f32_e32 v162, v162
	v_exp_f32_e32 v163, v163
	v_exp_f32_e32 v164, v164
	v_exp_f32_e32 v165, v165
	v_pk_add_f32 v[158:159], v[158:159], 1.0 op_sel_hi:[1,0]
	v_pk_add_f32 v[160:161], v[160:161], 1.0 op_sel_hi:[1,0]
	v_rcp_f32_e32 v158, v158
	v_rcp_f32_e32 v159, v159
	v_pk_add_f32 v[162:163], v[162:163], 1.0 op_sel_hi:[1,0]
	v_pk_add_f32 v[164:165], v[164:165], 1.0 op_sel_hi:[1,0]
	v_rcp_f32_e32 v160, v160
	v_rcp_f32_e32 v161, v161
	v_rcp_f32_e32 v162, v162
	v_rcp_f32_e32 v163, v163
	v_rcp_f32_e32 v164, v164
	v_rcp_f32_e32 v165, v165
	v_mad_i64_i32 v[156:157], s[18:19], s20, v153, 0
	v_pk_mul_f32 v[158:159], v[86:87], v[158:159]
	v_lshl_add_u64 v[156:157], v[156:157], 1, s[8:9]
	v_pk_mul_f32 v[158:159], v[70:71], v[158:159]
	v_pk_mul_f32 v[160:161], v[88:89], v[160:161]
	v_pk_mul_f32 v[162:163], v[78:79], v[162:163]
	v_pk_mul_f32 v[164:165], v[80:81], v[164:165]
	v_pk_mul_f32 v[160:161], v[72:73], v[160:161]
	v_pk_mul_f32 v[162:163], v[66:67], v[162:163]
	v_pk_mul_f32 v[164:165], v[68:69], v[164:165]
	v_lshl_add_u64 v[166:167], v[156:157], 0, v[142:143]
	v_cvt_pk_bf16_f32 v156, v158, v159
	v_cvt_pk_bf16_f32 v157, v160, v161
	v_cvt_pk_bf16_f32 v158, v162, v163
	v_cvt_pk_bf16_f32 v159, v164, v165
	s_waitcnt lgkmcnt(0)
	global_store_dwordx4 v[246:247], v[248:251], off
	ds_write_b128 v244, v[156:159]
	v_lshl_add_u64 v[246:247], v[166:167], 0, v[252:253]
	s_waitcnt lgkmcnt(0)
	ds_read_b128 v[248:251], v245
	v_pk_mul_f32 v[160:161], v[64:65], s[92:93] op_sel_hi:[1,0]
	v_pk_mul_f32 v[162:163], v[58:59], s[92:93] op_sel_hi:[1,0]
	v_pk_mul_f32 v[158:159], v[62:63], s[92:93] op_sel_hi:[1,0]
	v_pk_mul_f32 v[164:165], v[60:61], s[92:93] op_sel_hi:[1,0]
	v_exp_f32_e32 v158, v158
	v_exp_f32_e32 v159, v159
	v_exp_f32_e32 v160, v160
	v_exp_f32_e32 v161, v161
	v_exp_f32_e32 v162, v162
	v_exp_f32_e32 v163, v163
	v_exp_f32_e32 v164, v164
	v_exp_f32_e32 v165, v165
	v_pk_add_f32 v[158:159], v[158:159], 1.0 op_sel_hi:[1,0]
	v_pk_add_f32 v[160:161], v[160:161], 1.0 op_sel_hi:[1,0]
	v_rcp_f32_e32 v158, v158
	v_rcp_f32_e32 v159, v159
	v_pk_add_f32 v[162:163], v[162:163], 1.0 op_sel_hi:[1,0]
	v_pk_add_f32 v[164:165], v[164:165], 1.0 op_sel_hi:[1,0]
	v_rcp_f32_e32 v160, v160
	v_rcp_f32_e32 v161, v161
	v_rcp_f32_e32 v162, v162
	v_rcp_f32_e32 v163, v163
	v_rcp_f32_e32 v164, v164
	v_rcp_f32_e32 v165, v165
	v_mad_i64_i32 v[156:157], s[18:19], s20, v152, 0
	v_pk_mul_f32 v[158:159], v[62:63], v[158:159]
	v_lshl_add_u64 v[156:157], v[156:157], 1, s[8:9]
	v_pk_mul_f32 v[158:159], v[50:51], v[158:159]
	v_pk_mul_f32 v[160:161], v[64:65], v[160:161]
	v_pk_mul_f32 v[162:163], v[58:59], v[162:163]
	v_pk_mul_f32 v[164:165], v[60:61], v[164:165]
	v_pk_mul_f32 v[160:161], v[52:53], v[160:161]
	v_pk_mul_f32 v[162:163], v[42:43], v[162:163]
	v_pk_mul_f32 v[164:165], v[44:45], v[164:165]
	v_lshl_add_u64 v[166:167], v[156:157], 0, v[142:143]
	v_cvt_pk_bf16_f32 v156, v158, v159
	v_cvt_pk_bf16_f32 v157, v160, v161
	v_cvt_pk_bf16_f32 v158, v162, v163
	v_cvt_pk_bf16_f32 v159, v164, v165
	s_waitcnt lgkmcnt(0)
	global_store_dwordx4 v[246:247], v[248:251], off
	ds_write_b128 v244, v[156:159]
	v_lshl_add_u64 v[246:247], v[166:167], 0, v[252:253]
	s_waitcnt lgkmcnt(0)
	ds_read_b128 v[248:251], v245
	v_pk_mul_f32 v[160:161], v[56:57], s[92:93] op_sel_hi:[1,0]
	v_pk_mul_f32 v[162:163], v[46:47], s[92:93] op_sel_hi:[1,0]
	v_pk_mul_f32 v[158:159], v[54:55], s[92:93] op_sel_hi:[1,0]
	v_pk_mul_f32 v[164:165], v[48:49], s[92:93] op_sel_hi:[1,0]
	v_exp_f32_e32 v158, v158
	v_exp_f32_e32 v159, v159
	v_exp_f32_e32 v160, v160
	v_exp_f32_e32 v161, v161
	v_exp_f32_e32 v162, v162
	v_exp_f32_e32 v163, v163
	v_exp_f32_e32 v164, v164
	v_exp_f32_e32 v165, v165
	v_pk_add_f32 v[158:159], v[158:159], 1.0 op_sel_hi:[1,0]
	v_pk_add_f32 v[160:161], v[160:161], 1.0 op_sel_hi:[1,0]
	v_rcp_f32_e32 v158, v158
	v_rcp_f32_e32 v159, v159
	v_pk_add_f32 v[162:163], v[162:163], 1.0 op_sel_hi:[1,0]
	v_pk_add_f32 v[164:165], v[164:165], 1.0 op_sel_hi:[1,0]
	v_rcp_f32_e32 v160, v160
	v_rcp_f32_e32 v161, v161
	v_rcp_f32_e32 v162, v162
	v_rcp_f32_e32 v163, v163
	v_rcp_f32_e32 v164, v164
	v_rcp_f32_e32 v165, v165
	v_mad_i64_i32 v[156:157], s[18:19], s20, v151, 0
	v_pk_mul_f32 v[158:159], v[54:55], v[158:159]
	v_lshl_add_u64 v[156:157], v[156:157], 1, s[8:9]
	v_pk_mul_f32 v[158:159], v[34:35], v[158:159]
	v_pk_mul_f32 v[160:161], v[56:57], v[160:161]
	v_pk_mul_f32 v[162:163], v[46:47], v[162:163]
	v_pk_mul_f32 v[164:165], v[48:49], v[164:165]
	v_pk_mul_f32 v[160:161], v[36:37], v[160:161]
	v_pk_mul_f32 v[162:163], v[26:27], v[162:163]
	v_pk_mul_f32 v[164:165], v[28:29], v[164:165]
	v_lshl_add_u64 v[166:167], v[156:157], 0, v[142:143]
	v_cvt_pk_bf16_f32 v156, v158, v159
	v_cvt_pk_bf16_f32 v157, v160, v161
	v_cvt_pk_bf16_f32 v158, v162, v163
	v_cvt_pk_bf16_f32 v159, v164, v165
	s_waitcnt lgkmcnt(0)
	global_store_dwordx4 v[246:247], v[248:251], off
	ds_write_b128 v244, v[156:159]
	v_lshl_add_u64 v[246:247], v[166:167], 0, v[252:253]
	s_waitcnt lgkmcnt(0)
; __device__ __forceinline__ unsigned cvt_pk_bf16(float lo, float hi) { unsigned r; asm volatile("v_cvt_pk_bf16_f32 %0, %1, %2" : "=v"(r) : "v"(lo), "v"(hi)); return r; }
;     __device__ __forceinline__ void operator()(const f32x4 (&acc)[2][2][4][2], const Unit& u, int wr, int wc, int fr, int fq) const {
;     ...
;         const int col0 = u.pn * HALF + wc * 32 + 8 * fq;
; #pragma unroll
;         for (int ai = 0; ai < 2; ++ai)
; #pragma unroll
;             for (int m = 0; m < 4; ++m) { bf16_t* rowp = O + (size_t)(row0 + ai * HALF + m * 16) * ldc + col0;
;                 f32x2 h[4];
; #pragma unroll
;                 for (int n = 0; n < 2; ++n)
; #pragma unroll
;                     for (int j = 0; j < 2; ++j) { const f32x2 g = {acc[ai][0][m][n][2 * j], acc[ai][0][m][n][2 * j + 1]}, up = {acc[ai][1][m][n][2 * j], acc[ai][1][m][n][2 * j + 1]};
;                         const f32x2 t = g * (-1.44269504089f); f32x2 e; e.x = __builtin_amdgcn_exp2f(t.x); e.y = __builtin_amdgcn_exp2f(t.y);
;                         const f32x2 d = e + 1.0f; f32x2 r; r.x = __builtin_amdgcn_rcpf(d.x); r.y = __builtin_amdgcn_rcpf(d.y);
;                         h[n * 2 + j] = (g * r) * up; }
;                 u32x4 w; w.x = cvt_pk_bf16(h[0].x, h[0].y); w.y = cvt_pk_bf16(h[1].x, h[1].y); w.z = cvt_pk_bf16(h[2].x, h[2].y); w.w = cvt_pk_bf16(h[3].x, h[3].y);
;                 *(u32x4*)rowp = w; }
	ds_read_b128 v[248:251], v245
	v_pk_mul_f32 v[160:161], v[40:41], s[92:93] op_sel_hi:[1,0]
	v_pk_mul_f32 v[162:163], v[30:31], s[92:93] op_sel_hi:[1,0]
	v_pk_mul_f32 v[158:159], v[38:39], s[92:93] op_sel_hi:[1,0]
	v_pk_mul_f32 v[164:165], v[32:33], s[92:93] op_sel_hi:[1,0]
	v_exp_f32_e32 v158, v158
	v_exp_f32_e32 v159, v159
	v_exp_f32_e32 v160, v160
	v_exp_f32_e32 v161, v161
	v_exp_f32_e32 v162, v162
	v_exp_f32_e32 v163, v163
	v_exp_f32_e32 v164, v164
	v_exp_f32_e32 v165, v165
	v_pk_add_f32 v[158:159], v[158:159], 1.0 op_sel_hi:[1,0]
	v_pk_add_f32 v[160:161], v[160:161], 1.0 op_sel_hi:[1,0]
	v_rcp_f32_e32 v158, v158
	v_rcp_f32_e32 v159, v159
	v_pk_add_f32 v[162:163], v[162:163], 1.0 op_sel_hi:[1,0]
	v_pk_add_f32 v[164:165], v[164:165], 1.0 op_sel_hi:[1,0]
	v_rcp_f32_e32 v160, v160
	v_rcp_f32_e32 v161, v161
	v_rcp_f32_e32 v162, v162
	v_rcp_f32_e32 v163, v163
	v_rcp_f32_e32 v164, v164
	v_rcp_f32_e32 v165, v165
	v_mad_i64_i32 v[156:157], s[18:19], s20, v150, 0
	v_pk_mul_f32 v[158:159], v[38:39], v[158:159]
	v_lshl_add_u64 v[156:157], v[156:157], 1, s[8:9]
	v_pk_mul_f32 v[158:159], v[18:19], v[158:159]
	v_pk_mul_f32 v[160:161], v[40:41], v[160:161]
	v_pk_mul_f32 v[162:163], v[30:31], v[162:163]
	v_pk_mul_f32 v[164:165], v[32:33], v[164:165]
	v_pk_mul_f32 v[160:161], v[20:21], v[160:161]
	v_pk_mul_f32 v[162:163], v[10:11], v[162:163]
	v_pk_mul_f32 v[164:165], v[12:13], v[164:165]
	v_lshl_add_u64 v[166:167], v[156:157], 0, v[142:143]
	v_cvt_pk_bf16_f32 v156, v158, v159
	v_cvt_pk_bf16_f32 v157, v160, v161
	v_cvt_pk_bf16_f32 v158, v162, v163
	v_cvt_pk_bf16_f32 v159, v164, v165
	s_waitcnt lgkmcnt(0)
	global_store_dwordx4 v[246:247], v[248:251], off
	ds_write_b128 v244, v[156:159]
	v_lshl_add_u64 v[246:247], v[166:167], 0, v[252:253]
	s_waitcnt lgkmcnt(0)
	ds_read_b128 v[248:251], v245
	v_pk_mul_f32 v[160:161], v[24:25], s[92:93] op_sel_hi:[1,0]
	v_pk_mul_f32 v[162:163], v[14:15], s[92:93] op_sel_hi:[1,0]
	v_pk_mul_f32 v[158:159], v[22:23], s[92:93] op_sel_hi:[1,0]
	v_pk_mul_f32 v[164:165], v[16:17], s[92:93] op_sel_hi:[1,0]
	v_exp_f32_e32 v158, v158
	v_exp_f32_e32 v159, v159
	v_exp_f32_e32 v160, v160
	v_exp_f32_e32 v161, v161
	v_exp_f32_e32 v162, v162
	v_exp_f32_e32 v163, v163
	v_exp_f32_e32 v164, v164
	v_exp_f32_e32 v165, v165
	v_pk_add_f32 v[158:159], v[158:159], 1.0 op_sel_hi:[1,0]
	v_pk_add_f32 v[160:161], v[160:161], 1.0 op_sel_hi:[1,0]
	v_rcp_f32_e32 v158, v158
	v_rcp_f32_e32 v159, v159
	v_pk_add_f32 v[162:163], v[162:163], 1.0 op_sel_hi:[1,0]
	v_pk_add_f32 v[164:165], v[164:165], 1.0 op_sel_hi:[1,0]
	v_rcp_f32_e32 v160, v160
	v_rcp_f32_e32 v161, v161
	v_rcp_f32_e32 v162, v162
	v_rcp_f32_e32 v163, v163
	v_rcp_f32_e32 v164, v164
	v_rcp_f32_e32 v165, v165
	v_mad_i64_i32 v[156:157], s[18:19], s20, v149, 0
	v_lshl_add_u64 v[156:157], v[156:157], 1, s[8:9]
	v_pk_mul_f32 v[158:159], v[22:23], v[158:159]
	v_pk_mul_f32 v[160:161], v[24:25], v[160:161]
	v_pk_mul_f32 v[158:159], v[6:7], v[158:159]
	v_pk_mul_f32 v[162:163], v[14:15], v[162:163]
	v_pk_mul_f32 v[164:165], v[16:17], v[164:165]
	v_lshl_add_u64 v[142:143], v[156:157], 0, v[142:143]
	v_pk_mul_f32 v[160:161], v[8:9], v[160:161]
	v_pk_mul_f32 v[162:163], v[2:3], v[162:163]
	v_pk_mul_f32 v[164:165], v[4:5], v[164:165]
	v_cvt_pk_bf16_f32 v156, v158, v159
	v_cvt_pk_bf16_f32 v157, v160, v161
	v_cvt_pk_bf16_f32 v158, v162, v163
	s_mov_b64 s[38:39], 0
	v_cvt_pk_bf16_f32 v159, v164, v165
	s_waitcnt lgkmcnt(0)
	global_store_dwordx4 v[246:247], v[248:251], off
	ds_write_b128 v244, v[156:159]
	v_lshl_add_u64 v[246:247], v[142:143], 0, v[252:253]
	s_waitcnt lgkmcnt(0)
	ds_read_b128 v[248:251], v245
	s_waitcnt lgkmcnt(0)
	global_store_dwordx4 v[246:247], v[248:251], off
; __device__ __forceinline__ unsigned cvt_pk_bf16(float lo, float hi) { unsigned r; asm volatile("v_cvt_pk_bf16_f32 %0, %1, %2" : "=v"(r) : "v"(lo), "v"(hi)); return r; }
;     __device__ __forceinline__ void operator()(const f32x4 (&acc)[2][2][4][2], const Unit& u, int wr, int wc, int fr, int fq) const {
;     ...
;         if (!swiglu) {
;             const int col0 = u.pn * BM + wc * 32 + 8 * fq;
; #pragma unroll
;             for (int ai = 0; ai < 2; ++ai)
; #pragma unroll
;                 for (int m = 0; m < 4; ++m) { bf16_t* rowp = O + (size_t)(row0 + ai * HALF + m * 16) * ldc + col0;
; #pragma unroll
;                     for (int bj = 0; bj < 2; ++bj) { const f32x4 v0 = acc[ai][bj][m][0], v1 = acc[ai][bj][m][1];
;                         u32x4 w; w.x = cvt_pk_bf16(v0[0], v0[1]); w.y = cvt_pk_bf16(v0[2], v0[3]); w.z = cvt_pk_bf16(v1[0], v1[1]); w.w = cvt_pk_bf16(v1[2], v1[3]);
;                         *(u32x4*)(rowp + bj * HALF) = w; } }
.LBB0_365:
	s_andn2_b64 vcc, exec, s[38:39]
	s_cbranch_vccnz .LBB0_367
	v_lshl_or_b32 v142, s67, 8, v146
	v_ashrrev_i32_e32 v143, 31, v142
	v_lshlrev_b64 v[142:143], 1, v[142:143]
	v_lshl_add_u64 v[140:141], v[140:141], 0, v[142:143]
	v_cvt_pk_bf16_f32 v156, v126, v127
	v_cvt_pk_bf16_f32 v157, v128, v129
	v_cvt_pk_bf16_f32 v158, v122, v123
	v_cvt_pk_bf16_f32 v159, v124, v125
	ds_write_b128 v244, v[156:159]
	v_lshl_add_u64 v[246:247], v[140:141], 0, v[252:253]
	s_waitcnt lgkmcnt(0)
	ds_read_b128 v[248:251], v245
	s_nop 1
	v_cvt_pk_bf16_f32 v156, v114, v115
	v_cvt_pk_bf16_f32 v157, v116, v117
	v_cvt_pk_bf16_f32 v158, v106, v107
	v_cvt_pk_bf16_f32 v159, v108, v109
	s_waitcnt lgkmcnt(0)
	global_store_dwordx4 v[246:247], v[248:251], off
	ds_write_b128 v244, v[156:159]
	v_lshl_add_u64 v[246:247], v[140:141], 0, v[252:253]
	s_waitcnt lgkmcnt(0)
	ds_read_b128 v[248:251], v245
	v_mad_i64_i32 v[140:141], s[18:19], s20, v155, 0
	v_lshl_add_u64 v[140:141], v[140:141], 1, s[8:9]
	v_lshl_add_u64 v[140:141], v[140:141], 0, v[142:143]
	v_cvt_pk_bf16_f32 v156, v118, v119
	v_cvt_pk_bf16_f32 v157, v120, v121
	v_cvt_pk_bf16_f32 v158, v110, v111
	v_cvt_pk_bf16_f32 v159, v112, v113
	s_waitcnt lgkmcnt(0)
	global_store_dwordx4 v[246:247], v[248:251], off offset:256
	ds_write_b128 v244, v[156:159]
	v_lshl_add_u64 v[246:247], v[140:141], 0, v[252:253]
	s_waitcnt lgkmcnt(0)
	ds_read_b128 v[248:251], v245
	s_nop 1
	v_cvt_pk_bf16_f32 v156, v98, v99
	v_cvt_pk_bf16_f32 v157, v100, v101
	v_cvt_pk_bf16_f32 v158, v90, v91
	v_cvt_pk_bf16_f32 v159, v92, v93
	s_waitcnt lgkmcnt(0)
	global_store_dwordx4 v[246:247], v[248:251], off
	ds_write_b128 v244, v[156:159]
	v_lshl_add_u64 v[246:247], v[140:141], 0, v[252:253]
	s_waitcnt lgkmcnt(0)
	ds_read_b128 v[248:251], v245
	v_mad_i64_i32 v[140:141], s[18:19], s20, v154, 0
	v_lshl_add_u64 v[140:141], v[140:141], 1, s[8:9]
	v_lshl_add_u64 v[140:141], v[140:141], 0, v[142:143]
	v_cvt_pk_bf16_f32 v154, v102, v103
	v_cvt_pk_bf16_f32 v155, v104, v105
	v_cvt_pk_bf16_f32 v156, v94, v95
	v_cvt_pk_bf16_f32 v157, v96, v97
	s_waitcnt lgkmcnt(0)
	global_store_dwordx4 v[246:247], v[248:251], off offset:256
	ds_write_b128 v244, v[154:157]
	v_lshl_add_u64 v[246:247], v[140:141], 0, v[252:253]
	s_waitcnt lgkmcnt(0)
	ds_read_b128 v[248:251], v245
	s_nop 1
	v_cvt_pk_bf16_f32 v154, v82, v83
	v_cvt_pk_bf16_f32 v155, v84, v85
	v_cvt_pk_bf16_f32 v156, v74, v75
	v_cvt_pk_bf16_f32 v157, v76, v77
	s_waitcnt lgkmcnt(0)
	global_store_dwordx4 v[246:247], v[248:251], off
	ds_write_b128 v244, v[154:157]
	v_lshl_add_u64 v[246:247], v[140:141], 0, v[252:253]
	s_waitcnt lgkmcnt(0)
	ds_read_b128 v[248:251], v245
	v_mad_i64_i32 v[140:141], s[18:19], s20, v153, 0
	v_lshl_add_u64 v[140:141], v[140:141], 1, s[8:9]
	v_lshl_add_u64 v[140:141], v[140:141], 0, v[142:143]
	v_cvt_pk_bf16_f32 v154, v86, v87
	v_cvt_pk_bf16_f32 v155, v88, v89
	v_cvt_pk_bf16_f32 v156, v78, v79
	v_cvt_pk_bf16_f32 v157, v80, v81
	s_waitcnt lgkmcnt(0)
	global_store_dwordx4 v[246:247], v[248:251], off offset:256
	ds_write_b128 v244, v[154:157]
	v_lshl_add_u64 v[246:247], v[140:141], 0, v[252:253]
	s_waitcnt lgkmcnt(0)
	ds_read_b128 v[248:251], v245
	s_nop 1
	v_cvt_pk_bf16_f32 v154, v70, v71
	v_cvt_pk_bf16_f32 v155, v72, v73
	v_cvt_pk_bf16_f32 v156, v66, v67
	v_cvt_pk_bf16_f32 v157, v68, v69
	s_waitcnt lgkmcnt(0)
	global_store_dwordx4 v[246:247], v[248:251], off
	ds_write_b128 v244, v[154:157]
	v_lshl_add_u64 v[246:247], v[140:141], 0, v[252:253]
	s_waitcnt lgkmcnt(0)
	ds_read_b128 v[248:251], v245
	v_mad_i64_i32 v[140:141], s[18:19], s20, v152, 0
	v_lshl_add_u64 v[140:141], v[140:141], 1, s[8:9]
	v_lshl_add_u64 v[140:141], v[140:141], 0, v[142:143]
	v_cvt_pk_bf16_f32 v152, v62, v63
	v_cvt_pk_bf16_f32 v153, v64, v65
	v_cvt_pk_bf16_f32 v154, v58, v59
	v_cvt_pk_bf16_f32 v155, v60, v61
	s_waitcnt lgkmcnt(0)
	global_store_dwordx4 v[246:247], v[248:251], off offset:256
	ds_write_b128 v244, v[152:155]
	v_lshl_add_u64 v[246:247], v[140:141], 0, v[252:253]
	s_waitcnt lgkmcnt(0)
	ds_read_b128 v[248:251], v245
	s_nop 1
	v_cvt_pk_bf16_f32 v152, v50, v51
	v_cvt_pk_bf16_f32 v153, v52, v53
	v_cvt_pk_bf16_f32 v154, v42, v43
	v_cvt_pk_bf16_f32 v155, v44, v45
	s_waitcnt lgkmcnt(0)
	global_store_dwordx4 v[246:247], v[248:251], off
	ds_write_b128 v244, v[152:155]
	v_lshl_add_u64 v[246:247], v[140:141], 0, v[252:253]
	s_waitcnt lgkmcnt(0)
	ds_read_b128 v[248:251], v245
	v_mad_i64_i32 v[140:141], s[18:19], s20, v151, 0
	v_lshl_add_u64 v[140:141], v[140:141], 1, s[8:9]
	v_lshl_add_u64 v[140:141], v[140:141], 0, v[142:143]
	v_cvt_pk_bf16_f32 v152, v54, v55
	v_cvt_pk_bf16_f32 v153, v56, v57
	v_cvt_pk_bf16_f32 v154, v46, v47
	v_cvt_pk_bf16_f32 v155, v48, v49
	s_waitcnt lgkmcnt(0)
	global_store_dwordx4 v[246:247], v[248:251], off offset:256
	ds_write_b128 v244, v[152:155]
	v_lshl_add_u64 v[246:247], v[140:141], 0, v[252:253]
	s_waitcnt lgkmcnt(0)
	ds_read_b128 v[248:251], v245
	s_nop 1
	v_cvt_pk_bf16_f32 v152, v34, v35
	v_cvt_pk_bf16_f32 v153, v36, v37
	v_cvt_pk_bf16_f32 v154, v26, v27
	v_cvt_pk_bf16_f32 v155, v28, v29
	s_waitcnt lgkmcnt(0)
	global_store_dwordx4 v[246:247], v[248:251], off
	ds_write_b128 v244, v[152:155]
	v_lshl_add_u64 v[246:247], v[140:141], 0, v[252:253]
	s_waitcnt lgkmcnt(0)
	ds_read_b128 v[248:251], v245
	v_mad_i64_i32 v[140:141], s[18:19], s20, v150, 0
	v_lshl_add_u64 v[140:141], v[140:141], 1, s[8:9]
	v_lshl_add_u64 v[140:141], v[140:141], 0, v[142:143]
	v_cvt_pk_bf16_f32 v150, v38, v39
	v_cvt_pk_bf16_f32 v151, v40, v41
	v_cvt_pk_bf16_f32 v152, v30, v31
	v_cvt_pk_bf16_f32 v153, v32, v33
	s_waitcnt lgkmcnt(0)
	global_store_dwordx4 v[246:247], v[248:251], off offset:256
	ds_write_b128 v244, v[150:153]
	v_lshl_add_u64 v[246:247], v[140:141], 0, v[252:253]
	s_waitcnt lgkmcnt(0)
	ds_read_b128 v[248:251], v245
	s_nop 1
	v_cvt_pk_bf16_f32 v150, v18, v19
	v_cvt_pk_bf16_f32 v151, v20, v21
	v_cvt_pk_bf16_f32 v152, v10, v11
	v_cvt_pk_bf16_f32 v153, v12, v13
	s_waitcnt lgkmcnt(0)
	global_store_dwordx4 v[246:247], v[248:251], off
	ds_write_b128 v244, v[150:153]
	v_lshl_add_u64 v[246:247], v[140:141], 0, v[252:253]
	s_waitcnt lgkmcnt(0)
	ds_read_b128 v[248:251], v245
	v_mad_i64_i32 v[140:141], s[18:19], s20, v149, 0
	v_lshl_add_u64 v[140:141], v[140:141], 1, s[8:9]
	v_lshl_add_u64 v[150:151], v[140:141], 0, v[142:143]
	v_cvt_pk_bf16_f32 v140, v22, v23
	v_cvt_pk_bf16_f32 v141, v24, v25
	v_cvt_pk_bf16_f32 v142, v14, v15
	v_cvt_pk_bf16_f32 v143, v16, v17
	s_waitcnt lgkmcnt(0)
	global_store_dwordx4 v[246:247], v[248:251], off offset:256
	ds_write_b128 v244, v[140:143]
	v_lshl_add_u64 v[246:247], v[150:151], 0, v[252:253]
	s_waitcnt lgkmcnt(0)
	ds_read_b128 v[248:251], v245
	s_nop 1
	v_cvt_pk_bf16_f32 v140, v6, v7
	v_cvt_pk_bf16_f32 v141, v8, v9
	v_cvt_pk_bf16_f32 v142, v2, v3
	v_cvt_pk_bf16_f32 v143, v4, v5
	s_waitcnt lgkmcnt(0)
	global_store_dwordx4 v[246:247], v[248:251], off
	ds_write_b128 v244, v[140:143]
	v_lshl_add_u64 v[246:247], v[150:151], 0, v[252:253]
	s_waitcnt lgkmcnt(0)
	ds_read_b128 v[248:251], v245
	s_waitcnt lgkmcnt(0)
	global_store_dwordx4 v[246:247], v[248:251], off offset:256

; __device__ __forceinline__ unsigned cvt_pk_bf16(float lo, float hi) { unsigned r; asm volatile("v_cvt_pk_bf16_f32 %0, %1, %2" : "=v"(r) : "v"(lo), "v"(hi)); return r; }
;     __device__ __forceinline__ void operator()(const f32x4 (&acc)[2][2][4][2], const Unit& u, int wr, int wc, int fr, int fq) const {
;     ...
;         if (u.part >= 0) {
;             bf16_t* Pp = P + (size_t)u.part * pstride; const int col0 = u.pn * BM + wc * 32 + 8 * fq;
; #pragma unroll
;             for (int ai = 0; ai < 2; ++ai)
; #pragma unroll
;                 for (int m = 0; m < 4; ++m) { bf16_t* rowp = Pp + (size_t)(row0 + ai * HALF + m * 16 - prow0) * ldc + col0;
; #pragma unroll
;                     for (int bj = 0; bj < 2; ++bj) { const f32x4 v0 = acc[ai][bj][m][0], v1 = acc[ai][bj][m][1];
;                         u32x4 w; w.x = cvt_pk_bf16(v0[0], v0[1]); w.y = cvt_pk_bf16(v0[2], v0[3]); w.z = cvt_pk_bf16(v1[0], v1[1]); w.w = cvt_pk_bf16(v1[2], v1[3]);
;                         *(u32x4*)(rowp + bj * HALF) = w; } }
.LBB0_370:
	s_mov_b32 s31, s89
	s_lshl_b64 s[18:19], s[30:31], 23
	s_add_u32 s18, s70, s18
	v_lshl_or_b32 v140, s67, 8, v146
	s_addc_u32 s19, s71, s19
	v_ashrrev_i32_e32 v141, 31, v140
	v_add_u32_e32 v142, 0xffffc000, v148
	v_lshl_add_u64 v[140:141], v[140:141], 1, s[18:19]
	v_mad_i64_i32 v[142:143], s[18:19], s20, v142, 0
	v_lshl_add_u64 v[142:143], v[142:143], 1, v[140:141]
	v_cvt_pk_bf16_f32 v126, v126, v127
	v_cvt_pk_bf16_f32 v127, v128, v129
	v_cvt_pk_bf16_f32 v128, v122, v123
	v_cvt_pk_bf16_f32 v129, v124, v125
	ds_write_b128 v244, v[126:129]
	v_lshl_add_u64 v[246:247], v[142:143], 0, v[252:253]
	s_waitcnt lgkmcnt(0)
	ds_read_b128 v[248:251], v245
	v_cvt_pk_bf16_f32 v114, v114, v115
	v_cvt_pk_bf16_f32 v115, v116, v117
	v_cvt_pk_bf16_f32 v116, v106, v107
	v_add_u32_e32 v106, 0xffffc010, v148
	v_mad_i64_i32 v[106:107], s[18:19], s20, v106, 0
	v_cvt_pk_bf16_f32 v117, v108, v109
	s_waitcnt lgkmcnt(0)
	global_store_dwordx4 v[246:247], v[248:251], off
	ds_write_b128 v244, v[114:117]
	v_lshl_add_u64 v[246:247], v[142:143], 0, v[252:253]
	s_waitcnt lgkmcnt(0)
	ds_read_b128 v[248:251], v245
	s_nop 1
	v_lshl_add_u64 v[114:115], v[106:107], 1, v[140:141]
	v_cvt_pk_bf16_f32 v106, v118, v119
	v_cvt_pk_bf16_f32 v107, v120, v121
	v_cvt_pk_bf16_f32 v108, v110, v111
	v_cvt_pk_bf16_f32 v109, v112, v113
	s_waitcnt lgkmcnt(0)
	global_store_dwordx4 v[246:247], v[248:251], off offset:256
	ds_write_b128 v244, v[106:109]
	v_lshl_add_u64 v[246:247], v[114:115], 0, v[252:253]
	s_waitcnt lgkmcnt(0)
	ds_read_b128 v[248:251], v245
	v_cvt_pk_bf16_f32 v98, v98, v99
	v_cvt_pk_bf16_f32 v99, v100, v101
	v_cvt_pk_bf16_f32 v100, v90, v91
	v_add_u32_e32 v90, 0xffffc020, v148
	v_mad_i64_i32 v[90:91], s[18:19], s20, v90, 0
	v_cvt_pk_bf16_f32 v101, v92, v93
	s_waitcnt lgkmcnt(0)
	global_store_dwordx4 v[246:247], v[248:251], off
	ds_write_b128 v244, v[98:101]
	v_lshl_add_u64 v[246:247], v[114:115], 0, v[252:253]
	s_waitcnt lgkmcnt(0)
	ds_read_b128 v[248:251], v245
	s_nop 1
	v_lshl_add_u64 v[98:99], v[90:91], 1, v[140:141]
	v_cvt_pk_bf16_f32 v90, v102, v103
	v_cvt_pk_bf16_f32 v91, v104, v105
	v_cvt_pk_bf16_f32 v92, v94, v95
	v_cvt_pk_bf16_f32 v93, v96, v97
	s_waitcnt lgkmcnt(0)
	global_store_dwordx4 v[246:247], v[248:251], off offset:256
	ds_write_b128 v244, v[90:93]
	v_lshl_add_u64 v[246:247], v[98:99], 0, v[252:253]
	s_waitcnt lgkmcnt(0)
	ds_read_b128 v[248:251], v245
	v_cvt_pk_bf16_f32 v82, v82, v83
	v_cvt_pk_bf16_f32 v83, v84, v85
	v_cvt_pk_bf16_f32 v84, v74, v75
	v_add_u32_e32 v74, 0xffffc030, v148
	v_mad_i64_i32 v[74:75], s[18:19], s20, v74, 0
	v_cvt_pk_bf16_f32 v85, v76, v77
	s_waitcnt lgkmcnt(0)
	global_store_dwordx4 v[246:247], v[248:251], off
	ds_write_b128 v244, v[82:85]
	v_lshl_add_u64 v[246:247], v[98:99], 0, v[252:253]
	s_waitcnt lgkmcnt(0)
	ds_read_b128 v[248:251], v245
	s_nop 1
	v_lshl_add_u64 v[82:83], v[74:75], 1, v[140:141]
	v_cvt_pk_bf16_f32 v74, v86, v87
	v_cvt_pk_bf16_f32 v75, v88, v89
	v_cvt_pk_bf16_f32 v76, v78, v79
	v_cvt_pk_bf16_f32 v77, v80, v81
	s_waitcnt lgkmcnt(0)
	global_store_dwordx4 v[246:247], v[248:251], off offset:256
	ds_write_b128 v244, v[74:77]
	v_lshl_add_u64 v[246:247], v[82:83], 0, v[252:253]
	s_waitcnt lgkmcnt(0)
	ds_read_b128 v[248:251], v245
	v_cvt_pk_bf16_f32 v70, v70, v71
	v_cvt_pk_bf16_f32 v71, v72, v73
	v_cvt_pk_bf16_f32 v72, v66, v67
	v_add_u32_e32 v66, 0xffffc080, v148
	v_mad_i64_i32 v[66:67], s[18:19], s20, v66, 0
	v_lshl_add_u64 v[66:67], v[66:67], 1, v[140:141]
	v_cvt_pk_bf16_f32 v73, v68, v69
	s_waitcnt lgkmcnt(0)
	global_store_dwordx4 v[246:247], v[248:251], off
	ds_write_b128 v244, v[70:73]
	v_lshl_add_u64 v[246:247], v[82:83], 0, v[252:253]
	s_waitcnt lgkmcnt(0)
	ds_read_b128 v[248:251], v245
	v_cvt_pk_bf16_f32 v62, v62, v63
	v_cvt_pk_bf16_f32 v63, v64, v65
	v_cvt_pk_bf16_f32 v64, v58, v59
	v_cvt_pk_bf16_f32 v65, v60, v61
	s_waitcnt lgkmcnt(0)
	global_store_dwordx4 v[246:247], v[248:251], off offset:256
	ds_write_b128 v244, v[62:65]
	v_lshl_add_u64 v[246:247], v[66:67], 0, v[252:253]
	s_waitcnt lgkmcnt(0)
	ds_read_b128 v[248:251], v245
	v_cvt_pk_bf16_f32 v50, v50, v51
	v_cvt_pk_bf16_f32 v51, v52, v53
	v_cvt_pk_bf16_f32 v52, v42, v43
	v_add_u32_e32 v42, 0xffffc090, v148
	v_mad_i64_i32 v[42:43], s[18:19], s20, v42, 0
	v_cvt_pk_bf16_f32 v53, v44, v45
	s_waitcnt lgkmcnt(0)
	global_store_dwordx4 v[246:247], v[248:251], off
	ds_write_b128 v244, v[50:53]
	v_lshl_add_u64 v[246:247], v[66:67], 0, v[252:253]
	s_waitcnt lgkmcnt(0)
	ds_read_b128 v[248:251], v245
	s_nop 1
	v_lshl_add_u64 v[50:51], v[42:43], 1, v[140:141]
	v_cvt_pk_bf16_f32 v42, v54, v55
	v_cvt_pk_bf16_f32 v43, v56, v57
	v_cvt_pk_bf16_f32 v44, v46, v47
	v_cvt_pk_bf16_f32 v45, v48, v49
	s_waitcnt lgkmcnt(0)
	global_store_dwordx4 v[246:247], v[248:251], off offset:256
	ds_write_b128 v244, v[42:45]
	v_lshl_add_u64 v[246:247], v[50:51], 0, v[252:253]
	s_waitcnt lgkmcnt(0)
	ds_read_b128 v[248:251], v245
	v_cvt_pk_bf16_f32 v34, v34, v35
	v_cvt_pk_bf16_f32 v35, v36, v37
	v_cvt_pk_bf16_f32 v36, v26, v27
	v_add_u32_e32 v26, 0xffffc0a0, v148
	v_mad_i64_i32 v[26:27], s[18:19], s20, v26, 0
	v_cvt_pk_bf16_f32 v37, v28, v29
	s_waitcnt lgkmcnt(0)
	global_store_dwordx4 v[246:247], v[248:251], off
	ds_write_b128 v244, v[34:37]
	v_lshl_add_u64 v[246:247], v[50:51], 0, v[252:253]
	s_waitcnt lgkmcnt(0)
	ds_read_b128 v[248:251], v245
	s_nop 1
	v_lshl_add_u64 v[34:35], v[26:27], 1, v[140:141]
	v_cvt_pk_bf16_f32 v26, v38, v39
	v_cvt_pk_bf16_f32 v27, v40, v41
	v_cvt_pk_bf16_f32 v28, v30, v31
	v_cvt_pk_bf16_f32 v29, v32, v33
	s_waitcnt lgkmcnt(0)
	global_store_dwordx4 v[246:247], v[248:251], off offset:256
	ds_write_b128 v244, v[26:29]
	v_lshl_add_u64 v[246:247], v[34:35], 0, v[252:253]
	s_waitcnt lgkmcnt(0)
	ds_read_b128 v[248:251], v245
	v_cvt_pk_bf16_f32 v18, v18, v19
	v_cvt_pk_bf16_f32 v19, v20, v21
	v_cvt_pk_bf16_f32 v20, v10, v11
	v_add_u32_e32 v10, 0xffffc0b0, v148
	v_mad_i64_i32 v[10:11], s[18:19], s20, v10, 0
	v_cvt_pk_bf16_f32 v21, v12, v13
	s_waitcnt lgkmcnt(0)
	global_store_dwordx4 v[246:247], v[248:251], off
	ds_write_b128 v244, v[18:21]
	v_lshl_add_u64 v[246:247], v[34:35], 0, v[252:253]
	s_waitcnt lgkmcnt(0)
	ds_read_b128 v[248:251], v245
	s_nop 1
	v_lshl_add_u64 v[18:19], v[10:11], 1, v[140:141]
	v_cvt_pk_bf16_f32 v10, v22, v23
	v_cvt_pk_bf16_f32 v11, v24, v25
	v_cvt_pk_bf16_f32 v12, v14, v15
	v_cvt_pk_bf16_f32 v13, v16, v17
	s_waitcnt lgkmcnt(0)
	global_store_dwordx4 v[246:247], v[248:251], off offset:256
	ds_write_b128 v244, v[10:13]
	v_lshl_add_u64 v[246:247], v[18:19], 0, v[252:253]
	s_waitcnt lgkmcnt(0)
	ds_read_b128 v[248:251], v245
	v_cvt_pk_bf16_f32 v6, v6, v7
	v_cvt_pk_bf16_f32 v7, v8, v9
	v_cvt_pk_bf16_f32 v8, v2, v3
	v_cvt_pk_bf16_f32 v9, v4, v5
	s_waitcnt lgkmcnt(0)
	global_store_dwordx4 v[246:247], v[248:251], off
	ds_write_b128 v244, v[6:9]
	v_lshl_add_u64 v[246:247], v[18:19], 0, v[252:253]
	s_waitcnt lgkmcnt(0)
	ds_read_b128 v[248:251], v245
	s_and_b64 vcc, exec, s[40:41]
	s_mov_b64 s[30:31], -1
	s_waitcnt lgkmcnt(0)
	global_store_dwordx4 v[246:247], v[248:251], off offset:256
	s_cbranch_vccnz .LBB0_345
